# phase 1: the 6-tile GEMM workgroups with bit 3 set also convert their weight tiles first
# speedup vs baseline: 1.0225x; 1.0064x over previous
.LBB0_241:
	s_cmp_lt_i32 s94, 2
	s_cselect_b64 s[0:1], -1, 0
	s_and_b64 s[2:3], s[0:1], s[2:3]
	v_writelane_b32 v255, s66, 29
	s_andn2_b64 vcc, exec, s[2:3]
	s_nop 0
	v_writelane_b32 v255, s67, 30
	s_cbranch_vccnz .LBB0_699
	s_bfe_u32 s98, s97, 0x10003
	s_nop 0
	v_writelane_b32 v255, s98, 44
	s_nop 3

.Lp1_wcfirst:
	v_lshrrev_b32_e32 v1, 3, v0
	s_cmpk_lt_u32 s97, 0x40
	s_cbranch_scc1 .Lwc_heavy2
	s_add_u32 s8, s92, 0x2500000
	s_addc_u32 s9, s93, 0
	s_sub_i32 s40, s96, 64
	s_sub_i32 s41, s97, 64
	v_lshrrev_b32_e32 v1, 3, v0

.Lwc_again:
	s_cmp_eq_u32 s99, 0
	s_cbranch_scc1 .LBB0_699
	s_add_u32 s8, s92, 0x2500000
	s_addc_u32 s9, s93, 0
	s_mov_b32 s41, s99
	s_mov_b32 s99, 0
	s_movk_i32 s40, 64
	s_movk_i32 s98, 0x9c0
	s_branch .Lwc_go
.Lwc_heavy:
	v_readlane_b32 s98, v255, 44
	s_nop 3
	s_cmp_eq_u32 s98, 2
	s_cbranch_scc1 .LBB0_699
.Lwc_heavy2:
	s_add_u32 s8, s92, 0x2500000
	s_addc_u32 s9, s93, 0
	s_movk_i32 s40, 64
	s_add_i32 s41, s97, 0x500
	s_movk_i32 s98, 0xa80
	s_mov_b32 s99, 0
